# MLP-down tail tiles: 16 split-K parts of 8 K-tiles on 128 workgroups (variant of the 32-part version)
# baseline (speedup 1.0000x reference)
.LBB0_59:
	s_or_b64 exec, exec, s[4:5]
	s_add_u32 s4, s76, 0x800
	s_addc_u32 s5, s77, 0
	v_writelane_b32 v252, s4, 39
	s_add_u32 s3, s76, 0x10120000
	v_lshrrev_b32_e32 v165, 4, v164
	v_writelane_b32 v252, s5, 40
	v_writelane_b32 v252, s3, 41
	s_addc_u32 s3, s77, 0
	v_writelane_b32 v252, s3, 42
	s_add_u32 s3, s76, 0x10340000
	v_writelane_b32 v252, s3, 43
	s_addc_u32 s3, s77, 0
	s_add_u32 s4, s76, 0x1300000
	v_writelane_b32 v252, s3, 44
	s_addc_u32 s5, s77, 0
	v_writelane_b32 v252, s4, 45
	v_mbcnt_lo_u32_b32 v209, -1, 0
	v_lshl_add_u32 v204, v164, 4, 0
	v_writelane_b32 v252, s5, 46
	s_add_u32 s4, s76, 0x1b00000
	s_addc_u32 s5, s77, 0
	v_writelane_b32 v252, s4, 47
	v_mov_b32_e32 v205, 0x358637bd
	v_mov_b32_e32 v211, 1
	v_writelane_b32 v252, s5, 48
	s_add_u32 s4, s76, 0x3b00000
	s_addc_u32 s5, s77, 0
	v_writelane_b32 v252, s4, 49
	v_mov_b32_e32 v208, 0x3c23d70a
	v_mbcnt_hi_u32_b32 v210, -1, v209
	v_writelane_b32 v252, s5, 50
	s_add_u32 s4, s76, 0x5b00000
	s_addc_u32 s5, s77, 0
	v_writelane_b32 v252, s4, 51
	v_mov_b32_e32 v112, 0
	v_mov_b32_e32 v212, 0xf149f2ca
	v_writelane_b32 v252, s5, 52
	s_add_u32 s4, s76, 0x7300000
	s_addc_u32 s5, s77, 0
	v_writelane_b32 v252, s4, 53
	v_mov_b64_e32 v[174:175], 0xff
	v_mov_b64_e32 v[176:177], 0x440
	v_writelane_b32 v252, s5, 54
	s_add_u32 s4, s76, 0x7b00000
	s_addc_u32 s5, s77, 0
	v_writelane_b32 v252, s4, 55
	v_mov_b64_e32 v[178:179], 0x43f
	v_mov_b64_e32 v[180:181], 0x180
	v_writelane_b32 v252, s5, 56
	s_add_u32 s4, s76, 0x9b00000
	s_addc_u32 s5, s77, 0
	s_add_u32 s10, s76, 0x12100000
	s_addc_u32 s11, s77, 0
	s_add_u32 s86, s76, 0x16500000
	v_writelane_b32 v252, s4, 57
	s_addc_u32 s87, s77, 0
	v_mov_b64_e32 v[182:183], 0x17f
	v_writelane_b32 v252, s5, 58
	s_add_u32 s4, s76, 0x18700000
	s_addc_u32 s5, s77, 0
	v_writelane_b32 v252, s4, 59
	s_add_u32 s26, s76, 0x1a900000
	s_addc_u32 s27, s77, 0
	v_writelane_b32 v252, s5, 60
	s_ashr_i32 s31, s82, 31
	v_readlane_b32 s36, v252, 23
	s_ashr_i32 s3, s2, 31
	v_readlane_b32 s44, v252, 31
	v_readlane_b32 s45, v252, 32
	s_add_u32 s4, s44, 0x4000000
	s_addc_u32 s5, s45, 0
	v_readlane_b32 s37, v252, 24
	v_readlane_b32 s38, v252, 25
	v_readlane_b32 s39, v252, 26
	v_readlane_b32 s40, v252, 27
	v_readlane_b32 s41, v252, 28
	v_readlane_b32 s42, v252, 29
	v_readlane_b32 s43, v252, 30
	v_readlane_b32 s46, v252, 33
	v_readlane_b32 s47, v252, 34
	v_readlane_b32 s48, v252, 35
	v_readlane_b32 s49, v252, 36
	v_readlane_b32 s50, v252, 37
	v_readlane_b32 s51, v252, 38
	v_writelane_b32 v252, s4, 61
	s_add_u32 s18, s42, 0x2000
	s_addc_u32 s19, s43, 0
	v_writelane_b32 v252, s5, 62
	s_movk_i32 s91, 0x6000
	v_readlane_b32 s34, v252, 22
	s_lshl_b32 s74, s34, 2
	s_cmp_lg_u64 s[42:43], 0
	s_cselect_b64 s[20:21], -1, 0
	s_add_u32 s84, s76, 0x40200
	s_addc_u32 s85, s77, 0
	s_add_u32 s58, s76, 0x40400
	s_addc_u32 s59, s77, 0
	s_add_u32 s60, s76, 0x40500
	s_addc_u32 s61, s77, 0
	s_add_u32 s62, s76, 0x40600
	s_addc_u32 s63, s77, 0
	s_add_u32 s56, s76, 0x40700
	s_addc_u32 s57, s77, 0
	s_add_u32 s22, s76, 0x40800
	s_addc_u32 s23, s77, 0
	s_add_u32 s4, s76, 0x40900
	s_addc_u32 s5, s77, 0
	v_writelane_b32 v252, s4, 63
	v_writelane_b32 v255, s84, 0
	s_movk_i32 s94, 0x1fff
	v_writelane_b32 v253, s5, 0
	s_add_u32 s4, s76, 0x40a00
	s_addc_u32 s5, s77, 0
	v_writelane_b32 v253, s4, 1
	v_writelane_b32 v255, s85, 1
	v_writelane_b32 v255, s58, 2
	v_writelane_b32 v253, s5, 2
	s_add_u32 s4, s76, 0x40b00
	s_addc_u32 s5, s77, 0
	v_writelane_b32 v253, s4, 3
	v_writelane_b32 v255, s59, 3
	v_writelane_b32 v255, s60, 4
	v_writelane_b32 v253, s5, 4
	s_add_u32 s4, s76, 0x40c00
	s_addc_u32 s5, s77, 0
	v_writelane_b32 v253, s4, 5
	v_writelane_b32 v255, s61, 5
	v_writelane_b32 v255, s62, 6
	v_writelane_b32 v253, s5, 6
	s_add_u32 s4, s76, 0x40d00
	s_addc_u32 s5, s77, 0
	v_writelane_b32 v253, s4, 7
	v_writelane_b32 v255, s63, 7
	v_writelane_b32 v255, s56, 8
	v_writelane_b32 v253, s5, 8
	s_add_u32 s4, s76, 0x40e00
	s_addc_u32 s5, s77, 0
	v_writelane_b32 v253, s4, 9
	v_writelane_b32 v255, s57, 9
	s_nop 0
	v_writelane_b32 v253, s5, 10
	s_add_u32 s4, s76, 0x40f00
	s_addc_u32 s5, s77, 0
	v_writelane_b32 v253, s4, 11
	s_nop 1
	v_writelane_b32 v253, s5, 12
	s_add_u32 s4, s76, 0x41000
	s_addc_u32 s5, s77, 0
	v_writelane_b32 v253, s4, 13
	s_nop 1
	v_writelane_b32 v253, s5, 14
	s_add_u32 s4, s76, 0x41100
	s_addc_u32 s5, s77, 0
	v_writelane_b32 v253, s4, 15
	s_nop 1
	v_writelane_b32 v253, s5, 16
	s_add_u32 s4, s76, 0x41200
	s_addc_u32 s5, s77, 0
	v_writelane_b32 v253, s4, 17
	s_nop 1
	v_writelane_b32 v253, s5, 18
	s_add_u32 s4, s76, 0x41300
	s_addc_u32 s5, s77, 0
	v_writelane_b32 v253, s4, 19
	s_cmp_eq_u32 s8, 15
	s_nop 0
	v_writelane_b32 v253, s5, 20
	s_cselect_b64 s[4:5], -1, 0
	v_writelane_b32 v253, s4, 21
	s_cmp_eq_u32 s8, 14
	s_nop 0
	v_writelane_b32 v253, s5, 22
	s_cselect_b64 s[4:5], -1, 0
	v_writelane_b32 v253, s4, 23
	s_cmp_eq_u32 s8, 13
	s_nop 0
	v_writelane_b32 v253, s5, 24
	s_cselect_b64 s[4:5], -1, 0
	v_writelane_b32 v253, s4, 25
	s_cmp_eq_u32 s8, 12
	s_nop 0
	v_writelane_b32 v253, s5, 26
	s_cselect_b64 s[4:5], -1, 0
	v_writelane_b32 v253, s4, 27
	s_cmp_eq_u32 s8, 11
	s_nop 0
	v_writelane_b32 v253, s5, 28
	s_cselect_b64 s[4:5], -1, 0
	v_writelane_b32 v253, s4, 29
	s_cmp_eq_u32 s8, 10
	s_nop 0
	v_writelane_b32 v253, s5, 30
	s_cselect_b64 s[4:5], -1, 0
	v_writelane_b32 v253, s4, 31
	s_cmp_eq_u32 s8, 9
	s_nop 0
	v_writelane_b32 v253, s5, 32
	s_cselect_b64 s[4:5], -1, 0
	v_writelane_b32 v253, s4, 33
	s_cmp_eq_u32 s8, 8
	s_nop 0
	v_writelane_b32 v253, s5, 34
	s_cselect_b64 s[4:5], -1, 0
	v_writelane_b32 v253, s4, 35
	s_cmp_eq_u32 s8, 7
	s_nop 0
	v_writelane_b32 v253, s5, 36
	s_cselect_b64 s[4:5], -1, 0
	v_writelane_b32 v253, s4, 37
	s_cmp_eq_u32 s8, 6
	s_nop 0
	v_writelane_b32 v253, s5, 38
	s_cselect_b64 s[4:5], -1, 0
	v_writelane_b32 v253, s4, 39
	s_cmp_eq_u32 s8, 5
	s_nop 0
	v_writelane_b32 v253, s5, 40
	s_cselect_b64 s[4:5], -1, 0
	v_writelane_b32 v253, s4, 41
	s_cmp_eq_u32 s8, 4
	s_nop 0
	v_writelane_b32 v253, s5, 42
	s_cselect_b64 s[4:5], -1, 0
	v_writelane_b32 v253, s4, 43
	s_cmp_eq_u32 s8, 3
	s_nop 0
	v_writelane_b32 v253, s5, 44
	s_cselect_b64 s[4:5], -1, 0
	v_writelane_b32 v253, s4, 45
	s_cmp_eq_u32 s8, 2
	s_nop 0
	v_writelane_b32 v253, s5, 46
	s_cselect_b64 s[4:5], -1, 0
	v_writelane_b32 v253, s4, 47
	s_cmp_eq_u32 s8, 1
	s_nop 0
	v_writelane_b32 v253, s5, 48
	s_cselect_b64 s[4:5], -1, 0
	v_writelane_b32 v253, s4, 49
	s_cmp_eq_u32 s8, 0
	s_nop 0
	v_writelane_b32 v253, s5, 50
	s_cselect_b64 s[4:5], -1, 0
	v_writelane_b32 v253, s4, 51
	s_nop 1
	v_writelane_b32 v253, s5, 52
	s_lshl_b32 s4, s9, 2
	s_add_u32 s4, s16, s4
	s_addc_u32 s5, s17, 0
	s_add_u32 s6, s4, 0x1400
	s_addc_u32 s7, s5, 0
	v_writelane_b32 v253, s6, 53
	s_add_u32 s4, s4, 0x2400
	s_addc_u32 s5, s5, 0
	v_writelane_b32 v253, s7, 54
	v_writelane_b32 v253, s4, 55
	s_nop 1
	v_writelane_b32 v253, s5, 56
	s_add_u32 s4, s76, 0x43400
	s_addc_u32 s5, s77, 0
	v_writelane_b32 v253, s4, 57
	s_nop 1
	v_writelane_b32 v253, s5, 58
	s_add_u32 s4, s76, 0x43500
	s_addc_u32 s5, s77, 0
	v_writelane_b32 v253, s4, 59
	s_lshr_b32 s6, s25, 7
	s_bfe_u32 s7, s25, 0x10006
	v_writelane_b32 v253, s5, 60
	s_lshl_b32 s4, s34, 4
	s_and_b32 s28, s4, 0x3fffffe0
	s_lshl_b32 s4, s6, 14
	s_add_i32 s4, s4, 0
	v_writelane_b32 v253, s4, 61
	s_lshl_b32 s4, s2, 9
	v_writelane_b32 v253, s4, 62
	s_lshl_b32 s5, s7, 1
	s_lshl_b32 s4, s7, 6
	s_lshl_b32 s90, s7, 14
	s_add_i32 s29, 0, 0x20080
	s_and_b32 s8, 64, s25
	s_lshl_b32 s36, s82, 9
	s_cmp_eq_u32 s7, 0
	s_cselect_b64 s[12:13], -1, 0
	s_cmp_lg_u32 s8, 0
	v_writelane_b32 v253, s12, 63
	s_cselect_b64 s[8:9], -1, 0
	s_lshl_b32 s6, s6, 5
	v_writelane_b32 v254, s13, 0
	v_writelane_b32 v254, s8, 1
	s_cmpk_lt_i32 s2, 0x120
	v_lshl_add_u32 v203, v164, 2, s29
	v_writelane_b32 v254, s9, 2
	v_writelane_b32 v254, s6, 3
	s_cselect_b64 s[6:7], -1, 0
	v_writelane_b32 v254, s6, 4
	s_lshl_b32 s14, s2, 3
	s_add_i32 s16, s34, s14
	v_writelane_b32 v254, s7, 5
	s_lshr_b32 s6, s3, 29
	s_add_i32 s6, s2, s6
	s_ashr_i32 s30, s6, 3
	s_lshl_b32 s7, s2, 5
	s_mul_i32 s8, s30, 0xffffff01
	s_add_i32 s7, s8, s7
	s_ashr_i32 s8, s7, 31
	s_lshr_b32 s8, s8, 26
	s_add_i32 s8, s7, s8
	s_and_b32 s9, s8, 0xffffffc0
	s_sub_i32 s7, s7, s9
	s_bfe_i32 s9, s7, 0x80000
	s_bfe_u32 s9, s9, 0x3000c
	s_add_i32 s9, s7, s9
	s_and_b32 s12, s9, 0xf8
	s_sub_i32 s7, s7, s12
	s_ashr_i32 s8, s8, 6
	s_lshl_b32 s8, s8, 3
	s_sext_i32_i8 s7, s7
	s_add_i32 s8, s8, s7
	s_bfe_i32 s7, s9, 0x80000
	s_sext_i32_i16 s7, s7
	s_and_b32 s9, s2, 3
	s_lshl_b32 s14, s16, 6
	s_ashr_i32 s7, s7, 3
	s_bfe_u32 s12, s2, 0x30002
	s_lshl_b32 s13, s9, 10
	s_lshl_b32 s73, s82, 3
	v_writelane_b32 v254, s14, 6
	s_mov_b32 s14, s16
	v_writelane_b32 v254, s14, 7
	s_cmpk_lt_i32 s16, 0x800
	s_nop 0
	v_writelane_b32 v254, s15, 8
	s_cselect_b64 s[14:15], -1, 0
	v_writelane_b32 v254, s14, 9
	s_cmpk_lt_i32 s2, 0x420
	s_nop 0
	v_writelane_b32 v254, s15, 10
	s_cselect_b64 s[14:15], -1, 0
	s_and_b32 s6, s6, -8
	v_writelane_b32 v254, s14, 11
	s_sub_i32 s33, s2, s6
	s_nop 0
	v_writelane_b32 v254, s15, 12
	s_add_u32 s14, s46, 0x4000000
	s_addc_u32 s15, s47, 0
	v_readlane_b32 s40, v252, 0
	v_readlane_b32 s52, v252, 12
	v_readlane_b32 s53, v252, 13
	v_readlane_b32 s50, v252, 10
	v_readlane_b32 s51, v252, 11
	s_cmp_lg_u64 s[52:53], 0
	v_writelane_b32 v254, s14, 13
	s_cselect_b64 s[50:51], -1, 0
	s_cmpk_lt_i32 s2, 0x140
	v_writelane_b32 v254, s15, 14
	s_cselect_b64 s[14:15], -1, 0
	v_writelane_b32 v254, s14, 15
	s_bfe_u32 s6, s25, 0x30006
	s_lshl_b32 s17, s6, 8
	v_writelane_b32 v254, s15, 16
	s_and_b32 s14, s2, 7
	v_writelane_b32 v254, s17, 17
	s_lshl_b32 s17, s6, 2
	v_readlane_b32 s54, v252, 14
	v_readlane_b32 s55, v252, 15
	s_bfe_u32 s15, s2, 0x30003
	s_lshl_b32 s16, s14, 11
	v_writelane_b32 v254, s17, 18
	s_lshl_b32 s17, s6, 20
	s_mov_b64 s[54:55], s[22:23]
	s_add_u32 s22, s26, s17
	s_addc_u32 s23, s27, 0
	s_cmp_lt_i32 s33, 0
	s_movk_i32 s17, 0x85
	s_movk_i32 s17, 0x80
	s_mul_i32 s17, s33, s17
	v_writelane_b32 v254, s22, 19
	s_add_i32 s17, s17, s30
	s_add_i32 s22, s2, 0x320
	s_cmpk_ge_u32 s2, 0xe0
	s_cselect_b32 s17, s22, s17
	v_writelane_b32 v255, s54, 10
	v_writelane_b32 v254, s23, 20
	s_ashr_i32 s22, s17, 31
	s_lshr_b32 s22, s22, 24
	s_add_i32 s22, s17, s22
	s_and_b32 s23, s22, 0xffffff00
	s_ashr_i32 s22, s22, 8
	s_lshl_b32 s22, s22, 3
	s_sub_i32 s17, s17, s23
	s_sub_i32 s23, 33, s22
	s_min_i32 s23, s23, 8
	v_writelane_b32 v254, s33, 21
	s_cmpk_lt_i32 s2, 0x100
	v_writelane_b32 v254, s30, 22
	s_cselect_b32 s88, 0, s13
	v_writelane_b32 v254, s88, 23
	s_cselect_b32 s12, s7, s12
	s_cselect_b32 s7, s7, s15
	v_writelane_b32 v254, s89, 24
	v_writelane_b32 v254, s12, 25
	v_writelane_b32 v254, s7, 26
	s_cselect_b32 s7, s8, 32
	v_writelane_b32 v254, s7, 27
	s_cselect_b32 s7, -1, s9
	v_writelane_b32 v254, s7, 28
	s_cselect_b32 s7, -1, s14
	v_writelane_b32 v254, s7, 29
	s_cselect_b32 s7, 32, 8
	v_writelane_b32 v254, s7, 30
	s_cselect_b32 s7, 0x80, 16
	v_writelane_b32 v254, s7, 31
	s_sext_i32_i16 s7, s23
	v_cvt_f32_i32_e32 v0, s7
	v_cvt_f32_i32_e32 v1, s17
	s_cselect_b32 s88, 0, s16
	s_lshl_b32 s6, s6, 22
	v_rcp_iflag_f32_e32 v2, v0
	s_add_u32 s8, s26, s6
	v_writelane_b32 v254, s26, 32
	s_addc_u32 s9, s27, 0
	v_mul_f32_e32 v2, v1, v2
	v_writelane_b32 v254, s27, 33
	s_xor_b32 s6, s17, s7
	v_trunc_f32_e32 v2, v2
	v_writelane_b32 v254, s8, 34
	s_ashr_i32 s6, s6, 30
	v_fma_f32 v1, -v2, v0, v1
	v_writelane_b32 v254, s9, 35
	s_or_b32 s8, s6, 1
	v_cmp_ge_f32_e64 s[6:7], |v1|, |v0|
	v_cvt_i32_f32_e32 v0, v2
	s_and_b64 s[6:7], s[6:7], exec
	s_mul_i32 s6, s83, s82
	s_mul_i32 s6, s6, s24
	v_writelane_b32 v254, s6, 36
	s_cselect_b32 s6, s8, 0
	v_readfirstlane_b32 s7, v0
	s_add_i32 s6, s7, s6
	s_mul_i32 s7, s6, s23
	s_sub_i32 s7, s17, s7
	s_sext_i32_i16 s7, s7
	s_add_i32 s7, s22, s7
	v_writelane_b32 v254, s7, 37
	v_writelane_b32 v254, s29, 38
	s_sext_i32_i16 s6, s6
	v_writelane_b32 v254, s6, 39
	s_lshl_b32 s6, s34, 7
	v_writelane_b32 v254, s6, 40
	s_add_u32 s6, s76, 0x1a740000
	s_addc_u32 s7, s77, 0
	v_writelane_b32 v254, s6, 41
	s_lshl_b32 s5, s5, 2
	s_lshl_b32 s4, s4, 1
	v_writelane_b32 v254, s7, 42
	v_writelane_b32 v254, s5, 43
	v_writelane_b32 v254, s28, 44
	s_add_i32 s5, s28, 0x800
	v_writelane_b32 v254, s5, 45
	s_add_i32 s5, 0, 0x20040
	v_writelane_b32 v254, s5, 46
	s_add_i32 s5, 0, 0x20044
	v_writelane_b32 v254, s5, 47
	v_writelane_b32 v254, s4, 48
	v_cmp_gt_u32_e64 s[6:7], 3, v164
	s_ashr_i32 s37, s36, 31
	v_writelane_b32 v254, s5, 49
	s_add_i32 s4, 0, 0x20084
	v_writelane_b32 v254, s4, 50
	v_writelane_b32 v254, s6, 51
	s_lshl_b64 s[64:65], s[36:37], 4
	v_writelane_b32 v255, s55, 11
	v_writelane_b32 v254, s7, 52
	v_writelane_b32 v254, s88, 53
	s_lshl_b64 s[6:7], s[36:37], 7
	v_xor_b32_e32 v0, v165, v164
	v_writelane_b32 v254, s89, 54
	v_writelane_b32 v254, s6, 55
	v_writelane_b32 v255, s64, 12
	v_lshlrev_b32_e32 v1, 3, v0
	v_writelane_b32 v254, s7, 56
	s_mov_b64 s[6:7], -1
	v_writelane_b32 v254, s6, 57
	s_lshl_b64 s[92:93], s[36:37], 2
	v_writelane_b32 v255, s65, 13
	v_writelane_b32 v254, s7, 58
	v_writelane_b32 v254, s72, 59
	v_writelane_b32 v254, s73, 60
	v_writelane_b32 v254, s86, 61
	v_and_b32_e32 v2, 56, v1
	v_mov_b32_e32 v0, 0
	v_and_b32_e32 v4, 0x78, v1
	v_writelane_b32 v254, s87, 62
	v_writelane_b32 v255, s92, 14
	v_mov_b32_e32 v113, v0
	v_mov_b32_e32 v114, v0
	v_mov_b32_e32 v115, v0
	v_lshlrev_b32_e32 v166, 1, v4
	v_lshlrev_b32_e32 v168, 1, v2
	s_mov_b32 s83, 0xffff0000
	s_mov_b32 s12, 0x800000
	s_movk_i32 s13, 0x4400
	s_add_i32 s33, 0, 0x20000
	s_mov_b32 s22, 0x40000
	s_movk_i32 s23, 0x7fff
	s_mov_b32 s24, 0x80000
	s_mov_b32 s25, 0xc0000
	s_mov_b32 s29, 0x100000
	s_mov_b32 s14, 0x140000
	s_mov_b32 s15, 0x180000
	s_mov_b32 s28, 0x1c0000
	s_mov_b32 s30, 0x3e38aa3b
	s_mov_b32 s52, 0xf149f2ca
	s_mov_b32 s53, 0xc2800000
	s_mov_b64 s[4:5], 0
	s_mov_b64 s[26:27], 0x80
	s_mov_b32 s66, s89
	v_writelane_b32 v254, s74, 63
	v_writelane_b32 v255, s93, 15
	v_readlane_b32 s41, v252, 1
	v_readlane_b32 s42, v252, 2
	v_readlane_b32 s43, v252, 3
	v_readlane_b32 s44, v252, 4
	v_readlane_b32 s45, v252, 5
	v_readlane_b32 s46, v252, 6
	v_readlane_b32 s47, v252, 7
	v_readlane_b32 s48, v252, 8
	v_readlane_b32 s49, v252, 9
	s_branch .LBB0_63

.LBB0_845:
	s_add_i32 s63, s63, 1
	s_mul_i32 s7, s63, s31
	s_mul_hi_u32 s40, s63, s82
	s_add_i32 s40, s40, s7
	s_mul_i32 s7, s63, s82
	s_add_u32 s46, s7, s2
	s_addc_u32 s47, s40, s3
	v_cmp_gt_i64_e32 vcc, s[46:47], v[182:183]
	v_cmp_lt_i64_e64 s[40:41], s[46:47], v[180:181]
	s_cbranch_vccnz .LBB0_850
	v_cmp_gt_i64_e32 vcc, s[46:47], v[174:175]
	s_mov_b64 s[48:49], -1
	s_cbranch_vccz .LBB0_848
	s_and_b32 s64, s46, 15
	s_lshl_b32 s88, s64, 10
	s_bfe_u32 s44, s46, 0x30004
	s_mov_b64 s[48:49], 0
	s_mov_b64 s[84:85], s[88:89]

.LBB0_851:
	s_mov_b32 s65, 8
	s_mov_b32 s46, 32

.LBB0_876:
	s_lshl_b32 s7, s16, 6
	s_lshl_b32 s6, s6, 4
	s_add_i32 s6, s6, s7
	s_add_i32 s6, s6, s56
	s_addk_i32 s6, 0xf800
	s_ashr_i32 s7, s6, 31
	s_lshl_b64 s[6:7], s[6:7], 18
	s_waitcnt lgkmcnt(0)
	v_lshl_add_u64 v[150:151], v[144:145], 0, s[6:7]
	s_and_b64 vcc, exec, s[42:43]
	s_cbranch_vccz .Lmy_pr_mlpdown_done
	global_store_dwordx4 v[150:151], v[132:135], off
	global_store_dwordx4 v[150:151], v[128:131], off offset:16
	global_store_dwordx4 v[150:151], v[116:119], off offset:512
	global_store_dwordx4 v[150:151], v[102:105], off offset:528
	s_nop 1
	v_add_co_u32_e32 v102, vcc, 0x4000, v150
	s_nop 1
	v_addc_co_u32_e32 v103, vcc, 0, v151, vcc
	global_store_dwordx4 v[102:103], v[124:127], off
	global_store_dwordx4 v[102:103], v[120:123], off offset:16
	global_store_dwordx4 v[102:103], v[94:97], off offset:512
	global_store_dwordx4 v[102:103], v[86:89], off offset:528
	s_nop 1
	v_add_co_u32_e32 v86, vcc, 0x8000, v150
	s_nop 1
	v_addc_co_u32_e32 v87, vcc, 0, v151, vcc
	global_store_dwordx4 v[86:87], v[106:109], off
	global_store_dwordx4 v[86:87], v[98:101], off offset:16
	global_store_dwordx4 v[86:87], v[78:81], off offset:512
	global_store_dwordx4 v[86:87], v[74:77], off offset:528
	s_nop 1
	v_add_co_u32_e32 v74, vcc, 0xc000, v150
	s_nop 1
	v_addc_co_u32_e32 v75, vcc, 0, v151, vcc
	global_store_dwordx4 v[74:75], v[90:93], off
	global_store_dwordx4 v[74:75], v[82:85], off offset:16
	global_store_dwordx4 v[74:75], v[70:73], off offset:512
	global_store_dwordx4 v[74:75], v[66:69], off offset:528
	s_branch .Lmy_pr_mlpdown_done
	s_nop 1
	v_add_co_u32_e32 v66, vcc, 0x20000, v150
	s_nop 1
	v_addc_co_u32_e32 v67, vcc, 0, v151, vcc
	global_store_dwordx4 v[66:67], v[62:65], off
	global_store_dwordx4 v[66:67], v[58:61], off offset:16
	global_store_dwordx4 v[66:67], v[46:49], off offset:512
	global_store_dwordx4 v[66:67], v[38:41], off offset:528
	s_nop 1
	v_add_co_u32_e32 v38, vcc, 0x24000, v150
	s_nop 1
	v_addc_co_u32_e32 v39, vcc, 0, v151, vcc
	global_store_dwordx4 v[38:39], v[54:57], off
	global_store_dwordx4 v[38:39], v[50:53], off offset:16
	global_store_dwordx4 v[38:39], v[30:33], off offset:512
	global_store_dwordx4 v[38:39], v[22:25], off offset:528
	s_nop 1
	v_add_co_u32_e32 v22, vcc, 0x28000, v150
	s_nop 1
	v_addc_co_u32_e32 v23, vcc, 0, v151, vcc
	global_store_dwordx4 v[22:23], v[42:45], off
	global_store_dwordx4 v[22:23], v[34:37], off offset:16
	global_store_dwordx4 v[22:23], v[14:17], off offset:512
	global_store_dwordx4 v[22:23], v[10:13], off offset:528
	s_nop 1
	v_add_co_u32_e32 v10, vcc, 0x2c000, v150
	s_nop 1
	v_addc_co_u32_e32 v11, vcc, 0, v151, vcc
	global_store_dwordx4 v[10:11], v[26:29], off
	global_store_dwordx4 v[10:11], v[18:21], off offset:16
	global_store_dwordx4 v[10:11], v[6:9], off offset:512
	global_store_dwordx4 v[10:11], v[2:5], off offset:528

.LBB0_938:
	s_ashr_i32 s6, s16, 3
	s_cmpk_gt_i32 s6, 63
	s_cselect_b32 s99, 1, 0
	s_add_i32 s4, s6, 0x2000
	s_ashr_i32 s5, s4, 31
	s_lshl_b64 s[34:35], s[4:5], 12
	s_waitcnt lgkmcnt(0)
	v_lshl_add_u64 v[6:7], v[2:3], 0, s[34:35]
	global_load_dwordx2 v[192:193], v[6:7], off
	s_cmp_eq_u32 s99, 1
	s_cbranch_scc1 .Lmy_fx_mlpdown_zero
	s_ashr_i32 s7, s6, 31
	s_lshl_b64 s[6:7], s[6:7], 10
	v_lshl_add_u64 v[22:23], v[4:5], 0, s[6:7]
	s_mov_b32 s100, 0x200000
	global_load_dwordx4 v[32:35], v[22:23], off
	v_add_co_u32_e64 v194, s[38:39], s22, v22
	s_nop 1
	v_addc_co_u32_e64 v195, s[38:39], 0, v23, s[38:39]
	global_load_dwordx4 v[36:39], v[194:195], off
	v_add_co_u32_e64 v194, s[38:39], s24, v22
	s_nop 1
	v_addc_co_u32_e64 v195, s[38:39], 0, v23, s[38:39]
	global_load_dwordx4 v[40:43], v[194:195], off
	v_add_co_u32_e64 v194, s[38:39], s25, v22
	s_nop 1
	v_addc_co_u32_e64 v195, s[38:39], 0, v23, s[38:39]
	global_load_dwordx4 v[44:47], v[194:195], off
	v_add_co_u32_e64 v194, s[38:39], s29, v22
	s_nop 1
	v_addc_co_u32_e64 v195, s[38:39], 0, v23, s[38:39]
	global_load_dwordx4 v[48:51], v[194:195], off
	v_add_co_u32_e64 v194, s[38:39], s14, v22
	s_nop 1
	v_addc_co_u32_e64 v195, s[38:39], 0, v23, s[38:39]
	global_load_dwordx4 v[52:55], v[194:195], off
	v_add_co_u32_e64 v194, s[38:39], s15, v22
	s_nop 1
	v_addc_co_u32_e64 v195, s[38:39], 0, v23, s[38:39]
	global_load_dwordx4 v[56:59], v[194:195], off
	v_add_co_u32_e64 v194, s[38:39], s28, v22
	s_nop 1
	v_addc_co_u32_e64 v195, s[38:39], 0, v23, s[38:39]
	global_load_dwordx4 v[60:63], v[194:195], off
	v_add_co_u32_e64 v196, s[38:39], s100, v22
	s_nop 1
	v_addc_co_u32_e64 v197, s[38:39], 0, v23, s[38:39]
	global_load_dwordx4 v[64:67], v[196:197], off
	v_add_co_u32_e64 v194, s[38:39], s22, v196
	s_nop 1
	v_addc_co_u32_e64 v195, s[38:39], 0, v197, s[38:39]
	global_load_dwordx4 v[68:71], v[194:195], off
	v_add_co_u32_e64 v194, s[38:39], s24, v196
	s_nop 1
	v_addc_co_u32_e64 v195, s[38:39], 0, v197, s[38:39]
	global_load_dwordx4 v[72:75], v[194:195], off
	v_add_co_u32_e64 v194, s[38:39], s25, v196
	s_nop 1
	v_addc_co_u32_e64 v195, s[38:39], 0, v197, s[38:39]
	global_load_dwordx4 v[76:79], v[194:195], off
	v_add_co_u32_e64 v194, s[38:39], s29, v196
	s_nop 1
	v_addc_co_u32_e64 v195, s[38:39], 0, v197, s[38:39]
	global_load_dwordx4 v[80:83], v[194:195], off
	v_add_co_u32_e64 v194, s[38:39], s14, v196
	s_nop 1
	v_addc_co_u32_e64 v195, s[38:39], 0, v197, s[38:39]
	global_load_dwordx4 v[84:87], v[194:195], off
	v_add_co_u32_e64 v194, s[38:39], s15, v196
	s_nop 1
	v_addc_co_u32_e64 v195, s[38:39], 0, v197, s[38:39]
	global_load_dwordx4 v[88:91], v[194:195], off
	v_add_co_u32_e64 v194, s[38:39], s28, v196
	s_nop 1
	v_addc_co_u32_e64 v195, s[38:39], 0, v197, s[38:39]
	global_load_dwordx4 v[92:95], v[194:195], off
	s_waitcnt vmcnt(0)
	v_lshlrev_b32_e32 v18, 16, v192
	v_and_b32_e32 v19, 0xffff0000, v192
	v_lshlrev_b32_e32 v20, 16, v193
	v_and_b32_e32 v21, 0xffff0000, v193
	v_pk_add_f32 v[18:19], v[32:33], v[18:19]
	v_pk_add_f32 v[20:21], v[34:35], v[20:21]
	v_pk_add_f32 v[18:19], v[36:37], v[18:19]
	v_pk_add_f32 v[20:21], v[38:39], v[20:21]
	v_pk_add_f32 v[18:19], v[40:41], v[18:19]
	v_pk_add_f32 v[20:21], v[42:43], v[20:21]
	v_pk_add_f32 v[18:19], v[44:45], v[18:19]
	v_pk_add_f32 v[20:21], v[46:47], v[20:21]
	v_pk_add_f32 v[18:19], v[48:49], v[18:19]
	v_pk_add_f32 v[20:21], v[50:51], v[20:21]
	v_pk_add_f32 v[18:19], v[52:53], v[18:19]
	v_pk_add_f32 v[20:21], v[54:55], v[20:21]
	v_pk_add_f32 v[18:19], v[56:57], v[18:19]
	v_pk_add_f32 v[20:21], v[58:59], v[20:21]
	v_pk_add_f32 v[18:19], v[60:61], v[18:19]
	v_pk_add_f32 v[20:21], v[62:63], v[20:21]
	v_pk_add_f32 v[18:19], v[64:65], v[18:19]
	v_pk_add_f32 v[20:21], v[66:67], v[20:21]
	v_pk_add_f32 v[18:19], v[68:69], v[18:19]
	v_pk_add_f32 v[20:21], v[70:71], v[20:21]
	v_pk_add_f32 v[18:19], v[72:73], v[18:19]
	v_pk_add_f32 v[20:21], v[74:75], v[20:21]
	v_pk_add_f32 v[18:19], v[76:77], v[18:19]
	v_pk_add_f32 v[20:21], v[78:79], v[20:21]
	v_pk_add_f32 v[18:19], v[80:81], v[18:19]
	v_pk_add_f32 v[20:21], v[82:83], v[20:21]
	v_pk_add_f32 v[18:19], v[84:85], v[18:19]
	v_pk_add_f32 v[20:21], v[86:87], v[20:21]
	v_pk_add_f32 v[18:19], v[88:89], v[18:19]
	v_pk_add_f32 v[20:21], v[90:91], v[20:21]
	v_pk_add_f32 v[18:19], v[92:93], v[18:19]
	v_pk_add_f32 v[20:21], v[94:95], v[20:21]
	s_branch .Lmy_fx_mlpdown_join
